# combined: V-read interleave, K-read split, waves 4-7 early closing barrier, P0 rewrite (weights + x copy), final norm loads up front
# baseline (speedup 1.0000x reference)
; #define SBAR() __builtin_amdgcn_sched_barrier(0)
; #define KRD(f, d0, kb) asm volatile("ds_read_b128 %0, %2 offset:%3\n\tds_read_b128 %1, %2 offset:%4" : "=&v"(f.a), "=&v"(f.b) : "v"((kb) + koff[(d0) & 3]), "i"(((d0) >> 2) * 128), "i"(((d0) >> 2) * 128 + 8192) : "memory")
; #define QMM(f, d0) do { pA0 = __builtin_amdgcn_mfma_f32_32x32x16_bf16(f.a, qr[d0], pA0, 0, 0, 0); pA1 = __builtin_amdgcn_mfma_f32_32x32x16_bf16(f.b, qr[d0], pA1, 0, 0, 0); } while (0)
; #define LW(n) do { asm volatile("s_waitcnt lgkmcnt(" #n ")" ::: "memory"); SBAR(); } while (0)
; #define PP_BAR(VM) do { if (VM) { asm volatile("s_waitcnt vmcnt(4) lgkmcnt(0)\n\ts_barrier" ::: "memory"); } else { asm volatile("s_waitcnt vmcnt(0) lgkmcnt(0)\n\ts_barrier" ::: "memory"); } } while (0)
; #define PP_BAR_PLAIN() asm volatile("s_waitcnt lgkmcnt(0)\n\ts_barrier" ::: "memory")
;     ...
;         LW(10); pA0 = __builtin_amdgcn_mfma_f32_32x32x16_bf16(k0_.a, qr[0], negm, 0, 0, 0); pA1 = __builtin_amdgcn_mfma_f32_32x32x16_bf16(k0_.b, qr[0], negm, 0, 0, 0); SBAR(); KRD(k0_, 2, kb_);
;     ...
;         pA0 = f32x16{}; pA1 = f32x16{};
;         LW(10); QMM(k0_, 0); SBAR(); KRD(k0_, 2, kb_);
;     ...
;         LW(10); QMM(k1_, 1); SBAR(); KRD(k1_, 3, kb_);
;         LW(4);  pv_mm(o[0], fa_, pa0, pa1, pa2, pa3); SBAR(); pv_rd<1>(fb_, vb_);
;         LW(10); QMM(k0_, 2); SBAR(); KRD(k0_, 4, kb_);
;         LW(10); QMM(k1_, 3); SBAR(); KRD(k1_, 5, kb_);
;         LW(4);  pv_mm(o[1], fb_, pa0, pa1, pa2, pa3); SBAR(); pv_rd<2>(fa_, vb_);
;         LW(10); QMM(k0_, 4); SBAR(); KRD(k0_, 6, kb_);
;         LW(10); QMM(k1_, 5); SBAR(); KRD(k1_, 7, kb_);
;         LW(4);  pv_mm(o[2], fa_, pa0, pa1, pa2, pa3); SBAR(); pv_rd<3>(fb_, vb_);
;         LW(10); QMM(k0_, 6); SBAR();
;         LW(8);  QMM(k1_, 7); SBAR();
;         LW(0);  pv_mm(o[3], fb_, pa0, pa1, pa2, pa3);
;       } else pv_d0(o, VBUF(t), pa0, pa1, pa2, pa3);
;       if (t + 1 < NT) { if (grpB) PP_BAR(t + 3 < NT); else PP_BAR_PLAIN(); }
.LBB0_69:
	s_waitcnt lgkmcnt(10)
	v_mfma_f32_32x32x16_bf16 v[98:113], v[82:85], v[158:161], v[66:81]
	v_add_u32_e32 v217, s87, v237
	ds_read_b128 v[250:253], v217 offset:0x2000
	v_mfma_f32_32x32x16_bf16 v[82:97], v[202:205], v[158:161], v[66:81]
	ds_read_b128 v[202:205], v217 offset:0
	s_waitcnt lgkmcnt(10)
	v_mfma_f32_32x32x16_bf16 v[98:113], v[198:201], v[154:157], v[98:113]
	v_add_u32_e32 v206, s87, v236
	ds_read_b128 v[198:201], v206 offset:0x2000
	v_mfma_f32_32x32x16_bf16 v[82:97], v[194:197], v[154:157], v[82:97]
	ds_read_b128 v[194:197], v206 offset:0
	s_waitcnt lgkmcnt(4)
	v_mfma_f32_32x32x16_bf16 v[2:17], v[174:177], v[190:193], v[2:17]
	ds_read_b64_tr_b16 v[190:191], v246 offset:0x3200
	ds_read_b64_tr_b16 v[192:193], v246 offset:0x3a00
	v_mfma_f32_32x32x16_bf16 v[2:17], v[170:173], v[186:189], v[2:17]
	ds_read_b64_tr_b16 v[186:187], v246 offset:0x2200
	ds_read_b64_tr_b16 v[188:189], v246 offset:0x2a00
	v_mfma_f32_32x32x16_bf16 v[2:17], v[166:169], v[182:185], v[2:17]
	ds_read_b64_tr_b16 v[182:183], v246 offset:0x1200
	ds_read_b64_tr_b16 v[184:185], v246 offset:0x1a00
	v_mfma_f32_32x32x16_bf16 v[2:17], v[162:165], v[178:181], v[2:17]
	ds_read_b64_tr_b16 v[178:179], v246 offset:0x200
	ds_read_b64_tr_b16 v[180:181], v246 offset:0xa00
	s_waitcnt lgkmcnt(10)
	v_mfma_f32_32x32x16_bf16 v[98:113], v[202:205], v[150:153], v[98:113]
	ds_read_b128 v[202:205], v248 offset:0x80
	v_mfma_f32_32x32x16_bf16 v[82:97], v[250:253], v[150:153], v[82:97]
	ds_read_b128 v[250:253], v248 offset:0x2080
	s_waitcnt lgkmcnt(10)
	v_mfma_f32_32x32x16_bf16 v[98:113], v[194:197], v[146:149], v[98:113]
	ds_read_b128 v[194:197], v247 offset:0x80
	v_mfma_f32_32x32x16_bf16 v[82:97], v[198:201], v[146:149], v[82:97]
	ds_read_b128 v[198:201], v247 offset:0x2080
	s_waitcnt lgkmcnt(4)
	v_mfma_f32_32x32x16_bf16 v[50:65], v[174:177], v[178:181], v[50:65]
	ds_read_b64_tr_b16 v[178:179], v246 offset:0x400
	ds_read_b64_tr_b16 v[180:181], v246 offset:0xc00
	v_mfma_f32_32x32x16_bf16 v[50:65], v[170:173], v[182:185], v[50:65]
	ds_read_b64_tr_b16 v[182:183], v246 offset:0x1400
	ds_read_b64_tr_b16 v[184:185], v246 offset:0x1c00
	v_mfma_f32_32x32x16_bf16 v[50:65], v[166:169], v[186:189], v[50:65]
	ds_read_b64_tr_b16 v[186:187], v246 offset:0x2400
	ds_read_b64_tr_b16 v[188:189], v246 offset:0x2c00
	v_mfma_f32_32x32x16_bf16 v[50:65], v[162:165], v[190:193], v[50:65]
	ds_read_b64_tr_b16 v[190:191], v246 offset:0x3400
	ds_read_b64_tr_b16 v[192:193], v246 offset:0x3c00
	s_waitcnt lgkmcnt(10)
	v_mfma_f32_32x32x16_bf16 v[98:113], v[202:205], v[142:145], v[98:113]
	ds_read_b128 v[202:205], v217 offset:0x80
	v_mfma_f32_32x32x16_bf16 v[82:97], v[250:253], v[142:145], v[82:97]
	ds_read_b128 v[248:251], v217 offset:0x2080
	s_waitcnt lgkmcnt(10)
	v_mfma_f32_32x32x16_bf16 v[98:113], v[194:197], v[138:141], v[98:113]
	ds_read_b128 v[194:197], v206 offset:0x80
	v_mfma_f32_32x32x16_bf16 v[82:97], v[198:201], v[138:141], v[82:97]
	ds_read_b128 v[198:201], v206 offset:0x2080
	s_waitcnt lgkmcnt(4)
	v_mfma_f32_32x32x16_bf16 v[34:49], v[174:177], v[178:181], v[34:49]
	ds_read_b64_tr_b16 v[178:179], v246 offset:0x600
	ds_read_b64_tr_b16 v[180:181], v246 offset:0xe00
	v_mfma_f32_32x32x16_bf16 v[34:49], v[170:173], v[182:185], v[34:49]
	ds_read_b64_tr_b16 v[182:183], v246 offset:0x1600
	ds_read_b64_tr_b16 v[184:185], v246 offset:0x1e00
	v_mfma_f32_32x32x16_bf16 v[34:49], v[166:169], v[186:189], v[34:49]
	ds_read_b64_tr_b16 v[186:187], v246 offset:0x2600
	ds_read_b64_tr_b16 v[188:189], v246 offset:0x2e00
	v_mfma_f32_32x32x16_bf16 v[34:49], v[162:165], v[190:193], v[34:49]
	ds_read_b64_tr_b16 v[190:191], v246 offset:0x3600
	ds_read_b64_tr_b16 v[192:193], v246 offset:0x3e00
	s_waitcnt lgkmcnt(10)
	v_mfma_f32_32x32x16_bf16 v[98:113], v[202:205], v[134:137], v[98:113]
	v_mfma_f32_32x32x16_bf16 v[82:97], v[248:251], v[134:137], v[82:97]
	s_waitcnt lgkmcnt(8)
	v_mfma_f32_32x32x16_bf16 v[98:113], v[194:197], v[130:133], v[98:113]
	v_mfma_f32_32x32x16_bf16 v[82:97], v[198:201], v[130:133], v[82:97]
	s_and_b64 vcc, exec, s[0:1]
	s_cbranch_vccz .Leb_b
	s_waitcnt lgkmcnt(0)
	v_mfma_f32_32x32x16_bf16 v[18:33], v[174:177], v[178:181], v[18:33]
	v_mfma_f32_32x32x16_bf16 v[18:33], v[170:173], v[182:185], v[18:33]
	v_mfma_f32_32x32x16_bf16 v[18:33], v[166:169], v[186:189], v[18:33]
	v_mfma_f32_32x32x16_bf16 v[18:33], v[162:165], v[190:193], v[18:33]
	s_waitcnt lgkmcnt(0)
	s_barrier
